# hgB step loop: counted vmcnt so steps no longer wait on previous step's oib stores
# speedup vs baseline: 1.0076x; 1.0076x over previous
.LBB0_132:
	s_waitcnt vmcnt(27)
	v_lshlrev_b32_e32 v82, 16, v142
	v_and_b32_e32 v83, 0xffff0000, v142
	v_pk_fma_f32 v[144:145], v[144:145], v[70:71], v[82:83]
	v_lshlrev_b32_e32 v70, 16, v143
	v_and_b32_e32 v71, 0xffff0000, v143
	v_pk_fma_f32 v[142:143], v[178:179], v[72:73], v[70:71]
	s_waitcnt vmcnt(26)
	v_lshlrev_b32_e32 v70, 16, v138
	v_and_b32_e32 v71, 0xffff0000, v138
	v_pk_fma_f32 v[146:147], v[146:147], v[66:67], v[70:71]
	v_lshlrev_b32_e32 v66, 16, v139
	v_and_b32_e32 v67, 0xffff0000, v139
	v_pk_fma_f32 v[138:139], v[182:183], v[68:69], v[66:67]
	s_waitcnt vmcnt(25)
	v_lshlrev_b32_e32 v66, 16, v134
	v_and_b32_e32 v67, 0xffff0000, v134
	v_pk_fma_f32 v[148:149], v[148:149], v[54:55], v[66:67]
	v_lshlrev_b32_e32 v54, 16, v135
	v_and_b32_e32 v55, 0xffff0000, v135
	v_pk_fma_f32 v[134:135], v[176:177], v[56:57], v[54:55]
	s_waitcnt vmcnt(24)
	v_lshlrev_b32_e32 v54, 16, v128
	v_and_b32_e32 v55, 0xffff0000, v128
	v_pk_fma_f32 v[150:151], v[150:151], v[46:47], v[54:55]
	v_lshlrev_b32_e32 v46, 16, v129
	v_and_b32_e32 v47, 0xffff0000, v129
	v_pk_fma_f32 v[152:153], v[152:153], v[48:49], v[46:47]
	s_waitcnt vmcnt(23)
	v_lshlrev_b32_e32 v46, 16, v112
	v_and_b32_e32 v47, 0xffff0000, v112
	v_pk_fma_f32 v[164:165], v[164:165], v[38:39], v[46:47]
	v_lshlrev_b32_e32 v38, 16, v113
	v_and_b32_e32 v39, 0xffff0000, v113
	v_pk_fma_f32 v[168:169], v[168:169], v[40:41], v[38:39]
	s_waitcnt vmcnt(22)
	v_lshlrev_b32_e32 v38, 16, v110
	v_and_b32_e32 v39, 0xffff0000, v110
	v_pk_fma_f32 v[174:175], v[174:175], v[30:31], v[38:39]
	v_lshlrev_b32_e32 v30, 16, v111
	v_and_b32_e32 v31, 0xffff0000, v111
	v_pk_fma_f32 v[176:177], v[172:173], v[32:33], v[30:31]
	s_waitcnt vmcnt(21)
	v_lshlrev_b32_e32 v30, 16, v108
	v_and_b32_e32 v31, 0xffff0000, v108
	s_lshl_b32 s10, s28, 11
	v_pk_fma_f32 v[182:183], v[170:171], v[22:23], v[30:31]
	v_lshlrev_b32_e32 v22, 16, v109
	v_and_b32_e32 v23, 0xffff0000, v109
	v_pk_fma_f32 v[184:185], v[166:167], v[24:25], v[22:23]
	s_waitcnt vmcnt(20)
	v_lshlrev_b32_e32 v22, 16, v106
	v_and_b32_e32 v23, 0xffff0000, v106
	s_add_u32 s8, s46, s27
	v_pk_fma_f32 v[188:189], v[162:163], v[18:19], v[22:23]
	v_lshlrev_b32_e32 v18, 16, v107
	v_and_b32_e32 v19, 0xffff0000, v107
	s_addc_u32 s9, s47, s26
	v_pk_fma_f32 v[190:191], v[160:161], v[20:21], v[18:19]
	v_lshl_add_u64 v[18:19], v[102:103], 1, s[8:9]
	s_mov_b64 s[8:9], 0x1c000
	v_lshl_add_u64 v[128:129], v[18:19], 0, s[8:9]
	s_mov_b32 s24, 4
	s_mov_b32 s11, 30
	s_waitcnt vmcnt(0)
	s_branch .LBB0_134

.LBB0_134:
	s_add_i32 s25, s50, s24
	s_add_i32 s8, s25, 1
	s_ashr_i32 s9, s8, 31
	s_lshl_b64 s[26:27], s[8:9], 9
	s_waitcnt vmcnt(16)
	v_mov_b64_e32 v[112:113], v[28:29]
	v_lshl_add_u64 v[18:19], v[118:119], 0, s[26:27]
	s_lshl_b64 s[8:9], s[8:9], 15
	v_mov_b64_e32 v[110:111], v[26:27]
	v_lshl_add_u64 v[26:27], v[116:117], 0, s[8:9]
	global_load_dwordx4 v[70:73], v[18:19], off offset:448
	global_load_dwordx4 v[66:69], v[18:19], off offset:384
	global_load_dwordx4 v[54:57], v[18:19], off offset:320
	global_load_dwordx4 v[46:49], v[18:19], off offset:256
	global_load_dwordx4 v[38:41], v[18:19], off offset:192
	global_load_dwordx4 v[30:33], v[18:19], off offset:128
	global_load_dwordx4 v[22:25], v[18:19], off offset:64
	s_nop 0
	global_load_dwordx4 v[18:21], v[18:19], off
	s_nop 0
	global_load_dwordx2 v[186:187], v[26:27], off offset:3584
	global_load_dwordx2 v[180:181], v[26:27], off offset:3072
	global_load_dwordx2 v[178:179], v[26:27], off offset:2560
	global_load_dwordx2 v[172:173], v[26:27], off offset:2048
	global_load_dwordx2 v[170:171], v[26:27], off offset:1536
	global_load_dwordx2 v[166:167], v[26:27], off offset:1024
	global_load_dwordx2 v[162:163], v[26:27], off offset:512
	global_load_dwordx2 v[160:161], v[26:27], off
	s_or_b32 s8, s24, 1
	s_and_b32 s9, s8, 0xff
	s_mulk_i32 s9, 0xab
	s_bfe_u32 s9, s9, 0x70009
	s_mul_i32 s9, s9, 3
	s_sub_i32 s8, s8, s9
	s_and_b32 s8, s8, 0xff
	v_lshl_add_u32 v0, s8, 14, v223
	v_mov_b64_e32 v[108:109], v[36:37]
	v_mov_b64_e32 v[104:105], v[44:45]
	v_mov_b64_e32 v[100:101], v[52:53]
	v_mov_b64_e32 v[96:97], v[60:61]
	v_mov_b64_e32 v[92:93], v[64:65]
	v_mov_b64_e32 v[88:89], v[76:77]
	v_mov_b64_e32 v[84:85], v[80:81]
	ds_write_b128 v0, v[6:9]
	ds_write_b128 v0, v[2:5] offset:16
	v_mov_b64_e32 v[6:7], v[10:11]
	v_mov_b64_e32 v[2:3], v[14:15]
	v_mov_b64_e32 v[206:207], v[120:121]
	v_mov_b64_e32 v[204:205], v[122:123]
	v_mov_b64_e32 v[202:203], v[124:125]
	v_mov_b64_e32 v[200:201], v[126:127]
	v_mov_b64_e32 v[198:199], v[130:131]
	v_mov_b64_e32 v[196:197], v[132:133]
	v_mov_b64_e32 v[194:195], v[136:137]
	v_mov_b64_e32 v[192:193], v[140:141]
	v_mov_b64_e32 v[106:107], v[34:35]
	v_mov_b64_e32 v[102:103], v[42:43]
	v_mov_b64_e32 v[98:99], v[50:51]
	v_mov_b64_e32 v[94:95], v[58:59]
	v_mov_b64_e32 v[90:91], v[62:63]
	v_mov_b64_e32 v[86:87], v[74:75]
	v_mov_b64_e32 v[82:83], v[78:79]
	s_cmp_gt_u32 s24, 32
	v_mov_b64_e32 v[8:9], v[12:13]
	v_mov_b64_e32 v[4:5], v[16:17]
	s_cbranch_scc1 .LBB0_136
	global_load_dwordx4 v[2:5], v[128:129], off offset:16
	global_load_dwordx4 v[6:9], v[128:129], off
.LBB0_136:
	s_add_i32 s26, s11, 1
	s_add_i32 s27, s24, -4
	s_and_b64 s[8:9], s[40:41], exec
	s_cselect_b32 s8, s27, s26
	s_and_b32 s9, s24, 0xff
	s_mulk_i32 s9, 0xab
	s_bfe_u32 s9, s9, 0x70009
	s_mul_i32 s9, s9, 3
	s_sub_i32 s9, s24, s9
	s_and_b32 s9, s9, 0xff
	v_lshl_add_u32 v0, s9, 14, v224
	s_waitcnt lgkmcnt(0)
	s_barrier
	ds_read2st64_b64 v[34:37], v0 offset1:1
	ds_read2st64_b64 v[50:53], v0 offset0:2 offset1:3
	ds_read2st64_b64 v[62:65], v0 offset0:4 offset1:5
	ds_read2st64_b64 v[74:77], v0 offset0:6 offset1:7
	v_cvt_pk_bf16_f32 v26, v188, v189
	v_cvt_pk_bf16_f32 v27, v190, v191
	v_cvt_pk_bf16_f32 v28, v182, v183
	v_cvt_pk_bf16_f32 v29, v184, v185
	v_cvt_pk_bf16_f32 v42, v174, v175
	v_cvt_pk_bf16_f32 v43, v176, v177
	v_cvt_pk_bf16_f32 v44, v164, v165
	v_cvt_pk_bf16_f32 v45, v168, v169
	v_cvt_pk_bf16_f32 v58, v150, v151
	s_waitcnt lgkmcnt(3)
	v_mfma_f32_16x16x32_bf16 v[34:37], v[34:37], v[26:29], 0
	v_cvt_pk_bf16_f32 v59, v152, v153
	v_cvt_pk_bf16_f32 v60, v148, v149
	v_cvt_pk_bf16_f32 v61, v134, v135
	s_waitcnt lgkmcnt(2)
	v_mfma_f32_16x16x32_bf16 v[34:37], v[50:53], v[42:45], v[34:37]
	v_cvt_pk_bf16_f32 v50, v146, v147
	v_cvt_pk_bf16_f32 v51, v138, v139
	v_cvt_pk_bf16_f32 v52, v144, v145
	s_waitcnt lgkmcnt(1)
	v_mfma_f32_16x16x32_bf16 v[34:37], v[62:65], v[58:61], v[34:37]
	ds_read2st64_b64 v[62:65], v0 offset0:8 offset1:9
	v_cvt_pk_bf16_f32 v53, v142, v143
	ds_read2st64_b64 v[78:81], v0 offset0:12 offset1:13
	s_waitcnt lgkmcnt(2)
	v_mfma_f32_16x16x32_bf16 v[34:37], v[74:77], v[50:53], v[34:37]
	ds_read2st64_b64 v[74:77], v0 offset0:10 offset1:11
	ds_read2st64_b64 v[120:123], v0 offset0:20 offset1:21
	s_lshl_b32 s8, s8, 6
	s_waitcnt lgkmcnt(3)
	v_mfma_f32_16x16x32_bf16 v[62:65], v[62:65], v[26:29], 0
	s_add_i32 s8, s8, s10
	s_cmp_lt_u32 s24, 34
	v_mov_b64_e32 v[124:125], v[202:203]
	s_waitcnt lgkmcnt(1)
	v_mfma_f32_16x16x32_bf16 v[62:65], v[74:77], v[42:45], v[62:65]
	ds_read2st64_b64 v[74:77], v0 offset0:14 offset1:15
	v_mov_b64_e32 v[126:127], v[200:201]
	v_mov_b64_e32 v[130:131], v[198:199]
	v_mfma_f32_16x16x32_bf16 v[62:65], v[78:81], v[58:61], v[62:65]
	ds_read2st64_b64 v[78:81], v0 offset0:16 offset1:17
	v_mov_b64_e32 v[132:133], v[196:197]
	v_mov_b64_e32 v[136:137], v[194:195]
	s_waitcnt lgkmcnt(1)
	v_mfma_f32_16x16x32_bf16 v[62:65], v[74:77], v[50:53], v[62:65]
	ds_read2st64_b64 v[74:77], v0 offset0:18 offset1:19
	v_mov_b64_e32 v[140:141], v[192:193]
	s_waitcnt lgkmcnt(1)
	v_mfma_f32_16x16x32_bf16 v[78:81], v[78:81], v[26:29], 0
	s_waitcnt lgkmcnt(0)
	v_mfma_f32_16x16x32_bf16 v[74:77], v[74:77], v[42:45], v[78:81]
	s_nop 5
	ds_read2st64_b64 v[78:81], v0 offset0:22 offset1:23
	v_mfma_f32_16x16x32_bf16 v[74:77], v[120:123], v[58:61], v[74:77]
	ds_read2st64_b64 v[120:123], v0 offset0:24 offset1:25
	s_waitcnt lgkmcnt(1)
	v_mfma_f32_16x16x32_bf16 v[74:77], v[78:81], v[50:53], v[74:77]
	ds_read2st64_b64 v[78:81], v0 offset0:26 offset1:27
	s_waitcnt lgkmcnt(1)
	v_mfma_f32_16x16x32_bf16 v[26:29], v[120:123], v[26:29], 0
	ds_read2st64_b64 v[120:123], v0 offset0:28 offset1:29
	s_waitcnt lgkmcnt(1)
	v_mfma_f32_16x16x32_bf16 v[26:29], v[78:81], v[42:45], v[26:29]
	ds_read2st64_b64 v[42:45], v0 offset0:30 offset1:31
	v_mov_b64_e32 v[78:79], v[82:83]
	v_mov_b64_e32 v[80:81], v[84:85]
	s_waitcnt lgkmcnt(1)
	v_mfma_f32_16x16x32_bf16 v[26:29], v[120:123], v[58:61], v[26:29]
	v_mov_b64_e32 v[58:59], v[94:95]
	v_mov_b64_e32 v[120:121], v[206:207]
	v_mov_b64_e32 v[122:123], v[204:205]
	s_waitcnt lgkmcnt(0)
	v_mfma_f32_16x16x32_bf16 v[26:29], v[42:45], v[50:53], v[26:29]
	v_or_b32_e32 v42, s8, v225
	v_ashrrev_i32_e32 v43, 31, v42
	s_nop 7
	s_nop 7
	s_nop 3
	v_lshlrev_b64 v[42:43], 6, v[42:43]
	v_cvt_pk_bf16_f32 v0, v34, v1
	v_lshl_add_u64 v[42:43], v[114:115], 0, v[42:43]
	v_or_b32_e32 v34, s8, v226
	global_store_short v[42:43], v0, off
	v_cvt_pk_bf16_f32 v0, v35, v1
	v_ashrrev_i32_e32 v35, 31, v34
	v_lshlrev_b64 v[34:35], 6, v[34:35]
	v_lshl_add_u64 v[34:35], v[114:115], 0, v[34:35]
	global_store_short v[34:35], v0, off
	v_or_b32_e32 v34, s8, v227
	v_ashrrev_i32_e32 v35, 31, v34
	v_lshlrev_b64 v[34:35], 6, v[34:35]
	v_lshl_add_u64 v[34:35], v[114:115], 0, v[34:35]
	v_cvt_pk_bf16_f32 v0, v36, v1
	global_store_short v[34:35], v0, off
	v_or_b32_e32 v34, s8, v228
	v_ashrrev_i32_e32 v35, 31, v34
	v_lshlrev_b64 v[34:35], 6, v[34:35]
	v_lshl_add_u64 v[34:35], v[114:115], 0, v[34:35]
	v_cvt_pk_bf16_f32 v0, v37, v1
	global_store_short v[34:35], v0, off
	v_or_b32_e32 v34, s8, v229
	v_ashrrev_i32_e32 v35, 31, v34
	v_lshlrev_b64 v[34:35], 6, v[34:35]
	v_lshl_add_u64 v[34:35], v[114:115], 0, v[34:35]
	v_cvt_pk_bf16_f32 v0, v62, v1
	global_store_short v[34:35], v0, off
	v_or_b32_e32 v34, s8, v230
	v_ashrrev_i32_e32 v35, 31, v34
	v_lshlrev_b64 v[34:35], 6, v[34:35]
	v_lshl_add_u64 v[34:35], v[114:115], 0, v[34:35]
	v_cvt_pk_bf16_f32 v0, v63, v1
	global_store_short v[34:35], v0, off
	v_or_b32_e32 v34, s8, v231
	v_ashrrev_i32_e32 v35, 31, v34
	v_lshlrev_b64 v[34:35], 6, v[34:35]
	v_lshl_add_u64 v[34:35], v[114:115], 0, v[34:35]
	v_cvt_pk_bf16_f32 v0, v64, v1
	global_store_short v[34:35], v0, off
	v_or_b32_e32 v34, s8, v232
	v_ashrrev_i32_e32 v35, 31, v34
	v_lshlrev_b64 v[34:35], 6, v[34:35]
	v_lshl_add_u64 v[34:35], v[114:115], 0, v[34:35]
	v_cvt_pk_bf16_f32 v0, v65, v1
	global_store_short v[34:35], v0, off
	v_or_b32_e32 v34, s8, v233
	v_ashrrev_i32_e32 v35, 31, v34
	v_lshlrev_b64 v[34:35], 6, v[34:35]
	v_lshl_add_u64 v[34:35], v[114:115], 0, v[34:35]
	v_cvt_pk_bf16_f32 v0, v74, v1
	global_store_short v[34:35], v0, off
	v_or_b32_e32 v34, s8, v234
	v_ashrrev_i32_e32 v35, 31, v34
	v_lshlrev_b64 v[34:35], 6, v[34:35]
	v_lshl_add_u64 v[34:35], v[114:115], 0, v[34:35]
	v_cvt_pk_bf16_f32 v0, v75, v1
	global_store_short v[34:35], v0, off
	v_or_b32_e32 v34, s8, v235
	v_ashrrev_i32_e32 v35, 31, v34
	v_lshlrev_b64 v[34:35], 6, v[34:35]
	v_lshl_add_u64 v[34:35], v[114:115], 0, v[34:35]
	v_cvt_pk_bf16_f32 v0, v76, v1
	global_store_short v[34:35], v0, off
	v_or_b32_e32 v34, s8, v236
	v_ashrrev_i32_e32 v35, 31, v34
	v_lshlrev_b64 v[34:35], 6, v[34:35]
	v_lshl_add_u64 v[34:35], v[114:115], 0, v[34:35]
	v_cvt_pk_bf16_f32 v0, v77, v1
	global_store_short v[34:35], v0, off
	v_or_b32_e32 v34, s8, v237
	v_ashrrev_i32_e32 v35, 31, v34
	v_lshlrev_b64 v[34:35], 6, v[34:35]
	v_cvt_pk_bf16_f32 v0, v26, v1
	v_lshl_add_u64 v[34:35], v[114:115], 0, v[34:35]
	v_or_b32_e32 v26, s8, v238
	global_store_short v[34:35], v0, off
	v_cvt_pk_bf16_f32 v0, v27, v1
	v_ashrrev_i32_e32 v27, 31, v26
	v_lshlrev_b64 v[26:27], 6, v[26:27]
	v_lshl_add_u64 v[26:27], v[114:115], 0, v[26:27]
	global_store_short v[26:27], v0, off
	v_or_b32_e32 v26, s8, v239
	v_ashrrev_i32_e32 v27, 31, v26
	v_lshlrev_b64 v[26:27], 6, v[26:27]
	v_lshl_add_u64 v[26:27], v[114:115], 0, v[26:27]
	v_cvt_pk_bf16_f32 v0, v28, v1
	global_store_short v[26:27], v0, off
	v_or_b32_e32 v26, s8, v240
	v_ashrrev_i32_e32 v27, 31, v26
	v_lshlrev_b64 v[26:27], 6, v[26:27]
	v_lshl_add_u64 v[26:27], v[114:115], 0, v[26:27]
	v_cvt_pk_bf16_f32 v0, v29, v1
	global_store_short v[26:27], v0, off
	v_mov_b64_e32 v[26:27], v[110:111]
	v_mov_b64_e32 v[34:35], v[106:107]
	v_mov_b64_e32 v[42:43], v[102:103]
	v_mov_b64_e32 v[50:51], v[98:99]
	v_mov_b64_e32 v[62:63], v[90:91]
	v_mov_b64_e32 v[74:75], v[86:87]
	s_cselect_b64 s[8:9], -1, 0
	s_cmp_gt_u32 s24, 33
	v_mov_b64_e32 v[28:29], v[112:113]
	v_mov_b64_e32 v[36:37], v[108:109]
	v_mov_b64_e32 v[44:45], v[104:105]
	v_mov_b64_e32 v[52:53], v[100:101]
	v_mov_b64_e32 v[60:61], v[96:97]
	v_mov_b64_e32 v[64:65], v[92:93]
	v_mov_b64_e32 v[76:77], v[88:89]
	s_cbranch_scc1 .Lhgb_skipb1
	s_waitcnt vmcnt(40)
	s_add_i32 s26, s25, 2
	s_ashr_i32 s27, s26, 31
	s_lshl_b64 s[28:29], s[26:27], 15
	s_lshl_b64 s[26:27], s[26:27], 9
	v_lshl_add_u64 v[74:75], v[116:117], 0, s[28:29]
	v_lshl_add_u64 v[78:79], v[118:119], 0, s[26:27]
	global_load_dwordx4 v[26:29], v[78:79], off
	global_load_dwordx4 v[34:37], v[78:79], off offset:64
	global_load_dwordx2 v[120:121], v[74:75], off
	global_load_dwordx2 v[122:123], v[74:75], off offset:512
	global_load_dwordx2 v[124:125], v[74:75], off offset:1024
	global_load_dwordx2 v[126:127], v[74:75], off offset:1536
	global_load_dwordx4 v[42:45], v[78:79], off offset:128
	global_load_dwordx4 v[50:53], v[78:79], off offset:192
	global_load_dwordx4 v[58:61], v[78:79], off offset:256
	global_load_dwordx4 v[62:65], v[78:79], off offset:320
	global_load_dwordx2 v[130:131], v[74:75], off offset:2048
	global_load_dwordx2 v[132:133], v[74:75], off offset:2560
	global_load_dwordx2 v[136:137], v[74:75], off offset:3072
	global_load_dwordx2 v[140:141], v[74:75], off offset:3584
	s_nop 0
	global_load_dwordx4 v[74:77], v[78:79], off offset:384
	s_nop 0
	global_load_dwordx4 v[78:81], v[78:79], off offset:448
	s_branch .LBB0_138
.Lhgb_skipb1:
	s_waitcnt vmcnt(16)
.LBB0_138:
	s_add_i32 s26, s24, 1
	s_cmp_gt_u32 s26, 34
	s_cbranch_scc1 .LBB0_140
	s_add_i32 s24, s24, 2
	s_and_b32 s25, s24, 0xff
	s_mulk_i32 s25, 0xab
	s_bfe_u32 s25, s25, 0x70009
	s_mul_i32 s25, s25, 3
	s_sub_i32 s24, s24, s25
	s_and_b32 s24, s24, 0xff
	v_lshl_add_u32 v0, s24, 14, v223
	ds_write_b128 v0, v[10:13]
	ds_write_b128 v0, v[14:17] offset:16
.LBB0_140:
	s_waitcnt vmcnt(32)
	v_mov_b64_e32 v[12:13], v[8:9]
	v_mov_b64_e32 v[16:17], v[4:5]
	s_cmp_gt_u32 s26, 32
	v_mov_b64_e32 v[10:11], v[6:7]
	v_mov_b64_e32 v[14:15], v[2:3]
	s_cbranch_scc1 .LBB0_142
	s_mov_b64 s[24:25], 0x4000
	v_add_co_u32_e32 v10, vcc, 0x4000, v128
	v_lshl_add_u64 v[14:15], v[128:129], 0, s[24:25]
	s_nop 0
	v_addc_co_u32_e32 v11, vcc, 0, v129, vcc
	global_load_dwordx4 v[10:13], v[10:11], off
	s_nop 0
	global_load_dwordx4 v[14:17], v[14:15], off offset:16
